# combo with the streaming loop shifted by 32 bytes (code placement)
# speedup vs baseline: 1.0141x; 1.0061x over previous
.LBB0_1105:
	s_lshl_b32 s4, s12, 14
	s_add_i32 s4, s4, 0
	v_lshlrev_b32_e32 v140, 2, v139
	v_lshlrev_b32_e32 v141, 2, v138
	v_add3_u32 v241, s4, v140, v141
	s_add_i32 s4, 0, 0x10000
	v_add3_u32 v242, s4, v140, v141
	v_and_b32_e32 v140, 1, v135
	v_and_b32_e32 v135, 2, v135
	v_cmp_eq_u32_e64 s[6:7], 0, v135
	v_or_b32_e32 v135, v139, v138
	v_mov_b32_e32 v226, 0
	v_lshlrev_b32_e32 v138, 2, v135
	v_mov_b32_e32 v139, v226
	v_lshl_add_u64 v[138:139], s[72:73], 0, v[138:139]
	s_mov_b64 s[12:13], 0xde00000
	v_lshl_add_u64 v[228:229], v[138:139], 0, s[12:13]
	s_mov_b64 s[12:13], 0xdd00000
	v_lshl_add_u64 v[230:231], v[138:139], 0, s[12:13]
	s_add_u32 s12, s72, 0xf100
	s_addc_u32 s13, s73, 0
	v_lshl_add_u64 v[232:233], v[132:133], 1, s[14:15]
	s_add_u32 s14, s72, 0x4200
	s_addc_u32 s15, s73, 0
	v_lshl_add_u64 v[234:235], v[130:131], 2, s[16:17]
	s_add_u32 s16, s72, 0x4400
	s_addc_u32 s17, s73, 0
	s_add_u32 s18, s72, 0x4500
	s_addc_u32 s19, s73, 0
	s_add_u32 s20, s72, 0x4600
	s_addc_u32 s21, s73, 0
	s_add_u32 s22, s72, 0x4700
	s_addc_u32 s23, s73, 0
	s_add_u32 s24, s72, 0x4800
	s_addc_u32 s25, s73, 0
	s_add_u32 s26, s72, 0x4900
	s_addc_u32 s27, s73, 0
	s_add_u32 s28, s72, 0x4a00
	s_addc_u32 s29, s73, 0
	s_add_u32 s30, s72, 0x4b00
	s_addc_u32 s31, s73, 0
	s_add_u32 s34, s72, 0x4c00
	s_addc_u32 s35, s73, 0
	s_add_u32 s36, s72, 0x4d00
	s_addc_u32 s37, s73, 0
	s_add_u32 s40, s72, 0x4e00
	s_addc_u32 s41, s73, 0
	s_add_u32 s42, s72, 0x4f00
	s_addc_u32 s43, s73, 0
	s_add_u32 s44, s72, 0x5000
	s_addc_u32 s45, s73, 0
	s_add_u32 s46, s72, 0x5100
	s_addc_u32 s47, s73, 0
	s_add_u32 s48, s72, 0x5200
	s_addc_u32 s49, s73, 0
	s_add_u32 s52, s72, 0x5300
	s_addc_u32 s53, s73, 0
	s_add_u32 s66, s72, 0x7400
	v_lshlrev_b32_e32 v131, 2, v134
	s_addc_u32 s67, s73, 0
	v_lshl_or_b32 v130, v130, 10, v131
	v_mov_b32_e32 v131, v226
	s_add_u32 s70, s72, 0x7500
	v_lshl_add_u64 v[130:131], s[72:73], 0, v[130:131]
	s_mov_b64 s[38:39], 0xdf00000
	s_mov_b32 s50, 0
	s_mov_b32 s33, 4
	v_cmp_eq_u32_e64 s[4:5], 0, v140
	v_cmp_gt_u32_e64 s[8:9], 4, v137
	s_addc_u32 s71, s73, 0
	v_or_b32_e32 v243, 0x1000, v136
	v_lshl_add_u64 v[236:237], v[130:131], 0, s[38:39]
	v_mov_b32_e32 v248, 0xf149f2ca
	s_add_i32 s92, 0, 0x23fc0
	s_add_i32 s93, 0, 0x23fc4
	v_mov_b32_e32 v244, 0x2000
	v_mov_b32_e32 v245, 0x800
	s_branch .LBB0_1108
	s_nop 0
	s_nop 0
	s_nop 0
	s_nop 0
	s_nop 0
	s_nop 0
	s_nop 0
	s_nop 0
	s_nop 0
	s_nop 0
	s_nop 0
	s_nop 0
	s_nop 0
	s_nop 0

.LBB0_1210:
	s_or_b64 exec, exec, s[76:77]
	s_mov_b64 s[76:77], exec
	v_mbcnt_lo_u32_b32 v130, s76, 0
	v_mbcnt_hi_u32_b32 v130, s77, v130
	v_cmp_eq_u32_e32 vcc, 0, v130
	s_waitcnt vmcnt(0)
	buffer_inv sc1
	s_and_saveexec_b64 s[78:79], vcc
	s_cbranch_execz .LBB0_1106
	s_bcnt1_i32_b64 s54, s[76:77]
	v_mov_b32_e32 v130, s54
	global_atomic_add v244, v130, s[74:75] offset:1024
	s_branch .LBB0_1106
	s_nop 0
	s_nop 0
	s_nop 0
	s_nop 0
	s_nop 0
	s_nop 0
	s_nop 0
	s_nop 0
	s_nop 0
	s_nop 0
	s_nop 0
	s_nop 0
	s_nop 0
	s_nop 0
	s_nop 0
	s_nop 0
	s_nop 0
	s_nop 0
	s_nop 0
	s_nop 0
	s_nop 0
	s_nop 0
	s_nop 0
	s_nop 0
	s_nop 0
	s_nop 0
	s_nop 0
	s_nop 0
	s_nop 0
	s_nop 0
	s_nop 0
	s_nop 0
	s_nop 0
	s_nop 0
	s_nop 0
	s_nop 0
	s_nop 0
	s_nop 0
	s_nop 0
	s_nop 0
.LBB0_1212:
	s_waitcnt vmcnt(0)
	s_mov_b64 s[0:1], 0
	v_mbcnt_lo_u32_b32 v232, -1, 0
